# final LayerNorm f32 stores: permlane32_swap so each store writes 1 KB contiguous (full lines); P0 x->bf16 units load full lines
# speedup vs baseline: 1.0130x; 1.0130x over previous
; #define LAS __attribute__((address_space(3)))
; __global__ void __launch_bounds__(512, 2) fwd_megakernel(Args a) {
;     ...
;     const float* x_prompt = a.in[0]; const float* x_sample = a.in[1]; const float* rel_bias = a.in[2];
;     const float* w_in_ab = a.in[3]; const float* pool_w = a.in[4]; const float* pool_scale = a.in[5]; const float* w_out_ab = a.in[6];
;     const float* w_in_c = a.in[7]; const float* conv_w = a.in[8]; const float* w_out_c = a.in[9]; const float* ln_g = a.in[10]; const float* ln_b = a.in[11];
;     unsigned char* dout = (unsigned char*)a.out;
;     bf16_t* XB = (bf16_t*)(dout + DO_XB); bf16_t* OACC = XB;
;     bf16_t* WT1 = (bf16_t*)(dout + DO_WT1); bf16_t* WT2 = (bf16_t*)(dout + DO_WT2); bf16_t* WT3 = (bf16_t*)(dout + DO_WT3);
;     bf16_t* WT4 = (bf16_t*)(dout + DO_WT4); bf16_t* WT5 = (bf16_t*)(dout + DO_WT5);
;     bf16_t* RA = (bf16_t*)(a.ws + WS_H0); bf16_t* RB = (bf16_t*)(a.ws + WS_RB); float* LACC = (float*)(a.ws + WS_LACC); float* STAT = (float*)(a.ws + WS_STAT);
;     const int gw = bx * 8 + wave, NGW = G * 8;
;     const int gt = bx * 512 + tid, NGT = G * 512;
;     constexpr int BIG = 1 << 30;
;     unsigned* barw = (unsigned*)(a.ws + WS_BAR);
;     volatile LAS unsigned* lds_st = (volatile LAS unsigned*)(lds + LDS_BYTES - 64);
;     if (bx == 0) { for (int i = tid; i < XCD_BAR_WORDS; i += 512) barw[i] = 0u; }
;     if (tid < 2) lds_st[tid] = 0u;
;     __syncthreads();
;     for (int rep = 0; rep < (EXP == 3 ? 2 : 1); ++rep) {
;         LAS float* scr = (LAS float*)(lds + wave * 16384);
;         constexpr int I1 = 32 * 320, I2 = 48 * 64, I3 = 32 * 256, I4 = 32 * 64, I5 = 4 * 4 * 8;
;         for (int it = gw; it < I1 + I2 + I3 + I4 + I5; it += NGW) {
;             int r = it;
;             if (r < I1) { const int kb = r / 320, nb = r % 320; transpose_item(w_in_ab, 10240, 64 * kb, 32 * nb, WT1, 2048, 32 * nb, scr, lane); continue; } r -= I1;
;             if (r < I2) { const int kb = r / 64, nb = r % 64; transpose_item(w_out_ab, 2048, 64 * kb, 32 * nb, WT2, 3072, 32 * nb, scr, lane); continue; } r -= I2;
;             if (r < I3) { const int kb = r / 256, nb = r % 256; const int n0 = 32 * nb, part = n0 >> 11, chn = n0 & 2047;
;                 const int type = (part == 0 || part == 3) ? 1 : 0, bj = (part >= 2) ? 1 : 0;
;                 const int drow = 256 * (2 * (chn >> 7) + type) + 128 * bj + (chn & 127);
.LBB0_3:
	s_or_b64 exec, exec, s[2:3]
	s_load_dwordx16 s[44:59], s[0:1], 0x0
	s_lshr_b32 s0, s14, 6
	s_add_u32 s2, s92, 0x6000000
	s_addc_u32 s3, s93, 0
	s_add_u32 s4, s92, 0x8800000
	s_addc_u32 s5, s93, 0
	v_writelane_b32 v255, s4, 14
	v_lshlrev_b32_e32 v201, 3, v168
	s_waitcnt lgkmcnt(0)
	v_writelane_b32 v255, s5, 15
	s_add_u32 s4, s92, 0x9400000
	s_addc_u32 s5, s93, 0
	v_writelane_b32 v255, s4, 16
	s_barrier
	s_nop 0
	v_writelane_b32 v255, s5, 17
	s_add_u32 s4, s92, 0xb400000
	s_addc_u32 s5, s93, 0
	v_writelane_b32 v255, s4, 18
	s_add_u32 s8, s92, 0xbc00000
	s_addc_u32 s9, s93, 0
	v_writelane_b32 v255, s5, 19
	s_nop 0
	v_readlane_b32 s1, v255, 13
	s_lshl_b32 s1, s1, 3
	s_add_i32 s6, s0, s1
	v_writelane_b32 v255, s1, 20
	s_nop 0
	v_readlane_b32 s4, v255, 9
	v_readlane_b32 s5, v255, 10
	s_lshl_b32 s4, s4, 3
	v_writelane_b32 v255, s4, 21
	s_cmpk_gt_i32 s6, 0x5c7f
	s_nop 0
	v_writelane_b32 v255, s5, 22
	s_mov_b32 s4, s6
	v_writelane_b32 v255, s4, 23
	s_nop 1
	v_writelane_b32 v255, s5, 24
	v_readlane_b32 s60, v255, 23
	v_readlane_b32 s61, v255, 21
	v_readlane_b32 s82, v255, 2
	v_readlane_b32 s83, v255, 3
	v_readlane_b32 s84, v255, 14
	v_readlane_b32 s85, v255, 15
	v_readlane_b32 s86, v255, 16
	v_readlane_b32 s87, v255, 17
	v_readlane_b32 s88, v255, 18
	v_readlane_b32 s89, v255, 19
	v_and_b32_e32 v1, 63, v168
	v_readfirstlane_b32 s90, v168
	v_and_b32_e32 v252, 15, v1
	v_lshlrev_b32_e32 v2, 4, v252
	v_lshrrev_b32_e32 v253, 4, v1
	v_lshlrev_b32_e32 v68, 4, v253
	v_lshrrev_b32_e32 v69, 3, v1
	v_and_b32_e32 v254, 7, v1
	v_lshlrev_b32_e32 v128, 4, v254
	v_lshlrev_b32_e32 v170, 3, v1
	v_lshlrev_b32_e32 v171, 4, v1
	s_lshr_b32 s90, s90, 6
	s_lshl_b32 s90, s90, 13
	v_lshlrev_b32_e32 v180, 1, v253
	v_and_b32_e32 v181, 7, v252
	v_xor_b32_e32 v180, v180, v181
	v_lshlrev_b32_e32 v180, 4, v180
	v_lshl_add_u32 v180, v252, 9, v180
	v_add_u32_e32 v180, s90, v180
	v_xor_b32_e32 v181, 16, v180
	v_lshrrev_b32_e32 v252, 5, v1
	v_xor_b32_e32 v252, v254, v252
	v_lshlrev_b32_e32 v252, 4, v252
	v_lshl_add_u32 v252, v69, 7, v252
	v_add_u32_e32 v182, s90, v252
	v_xor_b32_e32 v200, 32, v182
	v_xor_b32_e32 v202, 64, v182
	v_xor_b32_e32 v203, 0x60, v182
	s_cmp_lt_u32 s60, 24128
	s_cbranch_scc0 .Lp0_done
	s_mov_b32 s62, s60
	s_cmp_lt_u32 s62, 11840
	s_cbranch_scc0 .Lp0_dx_a0
	s_mov_b32 s75, 1
	s_cmp_lt_u32 s62, 5120
	s_cbranch_scc0 .Lp0_d2_a0
	s_and_b32 s29, s62, 31
	s_lshr_b32 s30, s62, 5
	s_mul_i32 s31, s29, 2621440
	s_lshl_b32 s32, s30, 8
	s_add_u32 s31, s31, s32
	s_add_u32 s64, s50, s31
	s_addc_u32 s65, s51, 0
	s_mov_b32 s66, 40960
	s_mul_i32 s31, s30, 262144
	s_lshl_b32 s32, s29, 7
	s_add_u32 s31, s31, s32
	s_add_u32 s72, s2, s31
	s_addc_u32 s73, s3, 0
	s_movk_i32 s74, 0x1000
	s_branch .Lp0_dd_a0

; __global__ void __launch_bounds__(512, 2) fwd_megakernel(Args a) {
;     ...
;         for (size_t i = gt; i < (size_t)MT * DM / 8; i += (size_t)NGT * 4) {
;             f32x4 v0[4], v1[4];
; #pragma unroll
;             for (int u = 0; u < 4; ++u) { const size_t ii = i + (size_t)u * NGT; if (ii < (size_t)MT * DM / 8) { const size_t e = ii * 8; const float* src = e < (size_t)MP * DM ? x_prompt + e : x_sample + (e - (size_t)MP * DM);
;                 v0[u] = *(const f32x4*)src; v1[u] = *(const f32x4*)(src + 4); } }
.Lp0_lx_a0:
	global_load_dwordx4 v[80:83], v171, s[64:65] offset:0 nt
	global_load_dwordx4 v[84:87], v171, s[64:65] offset:1024 nt
	global_load_dwordx4 v[92:95], v171, s[64:65] offset:2048 nt
	global_load_dwordx4 v[96:99], v171, s[64:65] offset:3072 nt
	s_add_u32 s64, s64, 0x1000
	s_addc_u32 s65, s65, 0
	global_load_dwordx4 v[100:103], v171, s[64:65] offset:0 nt
	global_load_dwordx4 v[104:107], v171, s[64:65] offset:1024 nt
	global_load_dwordx4 v[108:111], v171, s[64:65] offset:2048 nt
	global_load_dwordx4 v[112:115], v171, s[64:65] offset:3072 nt
	s_add_u32 s64, s64, 0x1000
	s_addc_u32 s65, s65, 0
	global_load_dwordx4 v[116:119], v171, s[64:65] offset:0 nt
	global_load_dwordx4 v[136:139], v171, s[64:65] offset:1024 nt
	global_load_dwordx4 v[140:143], v171, s[64:65] offset:2048 nt
	global_load_dwordx4 v[144:147], v171, s[64:65] offset:3072 nt
	s_add_u32 s64, s64, 0x1000
	s_addc_u32 s65, s65, 0
	global_load_dwordx4 v[148:151], v171, s[64:65] offset:0 nt
	global_load_dwordx4 v[152:155], v171, s[64:65] offset:1024 nt
	global_load_dwordx4 v[156:159], v171, s[64:65] offset:2048 nt
	global_load_dwordx4 v[160:163], v171, s[64:65] offset:3072 nt

; __global__ void __launch_bounds__(512, 2) fwd_megakernel(Args a) {
;     ...
;         for (size_t i = gt; i < (size_t)MT * DM / 8; i += (size_t)NGT * 4) {
;             f32x4 v0[4], v1[4];
; #pragma unroll
;             for (int u = 0; u < 4; ++u) { const size_t ii = i + (size_t)u * NGT; if (ii < (size_t)MT * DM / 8) { const size_t e = ii * 8; const float* src = e < (size_t)MP * DM ? x_prompt + e : x_sample + (e - (size_t)MP * DM);
;                 v0[u] = *(const f32x4*)src; v1[u] = *(const f32x4*)(src + 4); } }
.Lp0_lx_b:
	global_load_dwordx4 v[184:187], v171, s[64:65] offset:0 nt
	global_load_dwordx4 v[188:191], v171, s[64:65] offset:1024 nt
	global_load_dwordx4 v[192:195], v171, s[64:65] offset:2048 nt
	global_load_dwordx4 v[196:199], v171, s[64:65] offset:3072 nt
	s_add_u32 s64, s64, 0x1000
	s_addc_u32 s65, s65, 0
	global_load_dwordx4 v[204:207], v171, s[64:65] offset:0 nt
	global_load_dwordx4 v[208:211], v171, s[64:65] offset:1024 nt
	global_load_dwordx4 v[212:215], v171, s[64:65] offset:2048 nt
	global_load_dwordx4 v[216:219], v171, s[64:65] offset:3072 nt
	s_add_u32 s64, s64, 0x1000
	s_addc_u32 s65, s65, 0
	global_load_dwordx4 v[220:223], v171, s[64:65] offset:0 nt
	global_load_dwordx4 v[224:227], v171, s[64:65] offset:1024 nt
	global_load_dwordx4 v[228:231], v171, s[64:65] offset:2048 nt
	global_load_dwordx4 v[232:235], v171, s[64:65] offset:3072 nt
	s_add_u32 s64, s64, 0x1000
	s_addc_u32 s65, s65, 0
	global_load_dwordx4 v[236:239], v171, s[64:65] offset:0 nt
	global_load_dwordx4 v[240:243], v171, s[64:65] offset:1024 nt
	global_load_dwordx4 v[244:247], v171, s[64:65] offset:2048 nt
	global_load_dwordx4 v[248:251], v171, s[64:65] offset:3072 nt

; __device__ __forceinline__ unsigned pk2(float lo, float hi) { return f2bf(lo) | (f2bf(hi) << 16); }
; __global__ void __launch_bounds__(512, 2) fwd_megakernel(Args a) {
;     ...
; #pragma unroll
;             for (int u = 0; u < 4; ++u) { const size_t ii = i + (size_t)u * NGT; if (ii < (size_t)MT * DM / 8) { const size_t e = ii * 8;
;                 u32x4 o; o.x = pk2(v0[u][0], v0[u][1]); o.y = pk2(v0[u][2], v0[u][3]); o.z = pk2(v1[u][0], v1[u][1]); o.w = pk2(v1[u][2], v1[u][3]);
;                 *(u32x4*)(XB + e) = o; } } }
.Lp0_px_a:
	v_cvt_pk_bf16_f32 v80, v80, v81
	v_cvt_pk_bf16_f32 v81, v82, v83
	global_store_dwordx2 v170, v[80:81], s[72:73] offset:0
	v_cvt_pk_bf16_f32 v84, v84, v85
	v_cvt_pk_bf16_f32 v85, v86, v87
	global_store_dwordx2 v170, v[84:85], s[72:73] offset:512
	v_cvt_pk_bf16_f32 v92, v92, v93
	v_cvt_pk_bf16_f32 v93, v94, v95
	global_store_dwordx2 v170, v[92:93], s[72:73] offset:1024
	v_cvt_pk_bf16_f32 v96, v96, v97
	v_cvt_pk_bf16_f32 v97, v98, v99
	global_store_dwordx2 v170, v[96:97], s[72:73] offset:1536
	v_cvt_pk_bf16_f32 v100, v100, v101
	v_cvt_pk_bf16_f32 v101, v102, v103
	global_store_dwordx2 v170, v[100:101], s[72:73] offset:2048
	v_cvt_pk_bf16_f32 v104, v104, v105
	v_cvt_pk_bf16_f32 v105, v106, v107
	global_store_dwordx2 v170, v[104:105], s[72:73] offset:2560
	v_cvt_pk_bf16_f32 v108, v108, v109
	v_cvt_pk_bf16_f32 v109, v110, v111
	global_store_dwordx2 v170, v[108:109], s[72:73] offset:3072
	v_cvt_pk_bf16_f32 v112, v112, v113
	v_cvt_pk_bf16_f32 v113, v114, v115
	global_store_dwordx2 v170, v[112:113], s[72:73] offset:3584
	s_add_u32 s72, s72, 0x1000
	s_addc_u32 s73, s73, 0
	v_cvt_pk_bf16_f32 v116, v116, v117
	v_cvt_pk_bf16_f32 v117, v118, v119
	global_store_dwordx2 v170, v[116:117], s[72:73] offset:0
	v_cvt_pk_bf16_f32 v136, v136, v137
	v_cvt_pk_bf16_f32 v137, v138, v139
	global_store_dwordx2 v170, v[136:137], s[72:73] offset:512
	v_cvt_pk_bf16_f32 v140, v140, v141
	v_cvt_pk_bf16_f32 v141, v142, v143
	global_store_dwordx2 v170, v[140:141], s[72:73] offset:1024
	v_cvt_pk_bf16_f32 v144, v144, v145
	v_cvt_pk_bf16_f32 v145, v146, v147
	global_store_dwordx2 v170, v[144:145], s[72:73] offset:1536
	v_cvt_pk_bf16_f32 v148, v148, v149
	v_cvt_pk_bf16_f32 v149, v150, v151
	global_store_dwordx2 v170, v[148:149], s[72:73] offset:2048
	v_cvt_pk_bf16_f32 v152, v152, v153
	v_cvt_pk_bf16_f32 v153, v154, v155
	global_store_dwordx2 v170, v[152:153], s[72:73] offset:2560
	v_cvt_pk_bf16_f32 v156, v156, v157
	v_cvt_pk_bf16_f32 v157, v158, v159
	global_store_dwordx2 v170, v[156:157], s[72:73] offset:3072
	v_cvt_pk_bf16_f32 v160, v160, v161
	v_cvt_pk_bf16_f32 v161, v162, v163
	global_store_dwordx2 v170, v[160:161], s[72:73] offset:3584

; __device__ __forceinline__ unsigned pk2(float lo, float hi) { return f2bf(lo) | (f2bf(hi) << 16); }
; __global__ void __launch_bounds__(512, 2) fwd_megakernel(Args a) {
;     ...
;         for (size_t i = gt; i < (size_t)MT * DM / 8; i += (size_t)NGT * 4) {
;             f32x4 v0[4], v1[4];
; #pragma unroll
;             for (int u = 0; u < 4; ++u) { const size_t ii = i + (size_t)u * NGT; if (ii < (size_t)MT * DM / 8) { const size_t e = ii * 8; const float* src = e < (size_t)MP * DM ? x_prompt + e : x_sample + (e - (size_t)MP * DM);
;                 v0[u] = *(const f32x4*)src; v1[u] = *(const f32x4*)(src + 4); } }
; #pragma unroll
;             for (int u = 0; u < 4; ++u) { const size_t ii = i + (size_t)u * NGT; if (ii < (size_t)MT * DM / 8) { const size_t e = ii * 8;
;                 u32x4 o; o.x = pk2(v0[u][0], v0[u][1]); o.y = pk2(v0[u][2], v0[u][3]); o.z = pk2(v1[u][0], v1[u][1]); o.w = pk2(v1[u][2], v1[u][3]);
;                 *(u32x4*)(XB + e) = o; } } }
.Lp0_px_b:
	v_cvt_pk_bf16_f32 v184, v184, v185
	v_cvt_pk_bf16_f32 v185, v186, v187
	global_store_dwordx2 v170, v[184:185], s[76:77] offset:0
	v_cvt_pk_bf16_f32 v188, v188, v189
	v_cvt_pk_bf16_f32 v189, v190, v191
	global_store_dwordx2 v170, v[188:189], s[76:77] offset:512
	v_cvt_pk_bf16_f32 v192, v192, v193
	v_cvt_pk_bf16_f32 v193, v194, v195
	global_store_dwordx2 v170, v[192:193], s[76:77] offset:1024
	v_cvt_pk_bf16_f32 v196, v196, v197
	v_cvt_pk_bf16_f32 v197, v198, v199
	global_store_dwordx2 v170, v[196:197], s[76:77] offset:1536
	v_cvt_pk_bf16_f32 v204, v204, v205
	v_cvt_pk_bf16_f32 v205, v206, v207
	global_store_dwordx2 v170, v[204:205], s[76:77] offset:2048
	v_cvt_pk_bf16_f32 v208, v208, v209
	v_cvt_pk_bf16_f32 v209, v210, v211
	global_store_dwordx2 v170, v[208:209], s[76:77] offset:2560
	v_cvt_pk_bf16_f32 v212, v212, v213
	v_cvt_pk_bf16_f32 v213, v214, v215
	global_store_dwordx2 v170, v[212:213], s[76:77] offset:3072
	v_cvt_pk_bf16_f32 v216, v216, v217
	v_cvt_pk_bf16_f32 v217, v218, v219
	global_store_dwordx2 v170, v[216:217], s[76:77] offset:3584
	s_add_u32 s76, s76, 0x1000
	s_addc_u32 s77, s77, 0
	v_cvt_pk_bf16_f32 v220, v220, v221
	v_cvt_pk_bf16_f32 v221, v222, v223
	global_store_dwordx2 v170, v[220:221], s[76:77] offset:0
	v_cvt_pk_bf16_f32 v224, v224, v225
	v_cvt_pk_bf16_f32 v225, v226, v227
	global_store_dwordx2 v170, v[224:225], s[76:77] offset:512
	v_cvt_pk_bf16_f32 v228, v228, v229
	v_cvt_pk_bf16_f32 v229, v230, v231
	global_store_dwordx2 v170, v[228:229], s[76:77] offset:1024
	v_cvt_pk_bf16_f32 v232, v232, v233
	v_cvt_pk_bf16_f32 v233, v234, v235
	global_store_dwordx2 v170, v[232:233], s[76:77] offset:1536
	v_cvt_pk_bf16_f32 v236, v236, v237
	v_cvt_pk_bf16_f32 v237, v238, v239
	global_store_dwordx2 v170, v[236:237], s[76:77] offset:2048
	v_cvt_pk_bf16_f32 v240, v240, v241
	v_cvt_pk_bf16_f32 v241, v242, v243
	global_store_dwordx2 v170, v[240:241], s[76:77] offset:2560
	v_cvt_pk_bf16_f32 v244, v244, v245
	v_cvt_pk_bf16_f32 v245, v246, v247
	global_store_dwordx2 v170, v[244:245], s[76:77] offset:3072
	v_cvt_pk_bf16_f32 v248, v248, v249
	v_cvt_pk_bf16_f32 v249, v250, v251
	global_store_dwordx2 v170, v[248:249], s[76:77] offset:3584

.LBB0_1047:
	s_or_b64 exec, exec, s[0:1]
	v_mov_b32_e32 v64, v202
	s_and_b64 vcc, exec, s[14:15]
	s_waitcnt lgkmcnt(0)
	s_barrier
	s_cbranch_vccz .LBB0_1052
	v_readlane_b32 s0, v255, 0
	v_readlane_b32 s4, v255, 4
	v_readlane_b32 s1, v255, 1
	v_readlane_b32 s5, v255, 5
	s_add_u32 s0, s4, 0x2000
	v_lshlrev_b32_e32 v48, 3, v64
	v_readlane_b32 s2, v255, 2
	v_readlane_b32 s6, v255, 6
	s_addc_u32 s1, s5, 0
	v_ashrrev_i32_e32 v49, 31, v48
	v_readlane_b32 s3, v255, 3
	v_readlane_b32 s7, v255, 7
	s_add_u32 s2, s6, 0x2000
	v_lshlrev_b64 v[96:97], 2, v[48:49]
	s_addc_u32 s3, s7, 0
	v_lshl_add_u64 v[16:17], s[0:1], 0, v[96:97]
	v_lshl_add_u64 v[18:19], s[2:3], 0, v[96:97]
	global_load_dwordx4 v[0:3], v[16:17], off offset:16
	global_load_dwordx4 v[4:7], v[16:17], off
	global_load_dwordx4 v[8:11], v[18:19], off offset:16
	global_load_dwordx4 v[12:15], v[18:19], off
	v_add_u32_e32 v16, 0x200, v48
	v_ashrrev_i32_e32 v17, 31, v16
	v_lshlrev_b64 v[16:17], 2, v[16:17]
	v_lshl_add_u64 v[32:33], s[0:1], 0, v[16:17]
	v_lshl_add_u64 v[34:35], s[2:3], 0, v[16:17]
	global_load_dwordx4 v[16:19], v[32:33], off offset:16
	global_load_dwordx4 v[20:23], v[32:33], off
	global_load_dwordx4 v[24:27], v[34:35], off offset:16
	global_load_dwordx4 v[28:31], v[34:35], off
	v_add_u32_e32 v32, 0x400, v48
	v_add_u32_e32 v48, 0x600, v48
	v_ashrrev_i32_e32 v33, 31, v32
	v_ashrrev_i32_e32 v49, 31, v48
	v_lshlrev_b64 v[98:99], 2, v[32:33]
	v_lshlrev_b64 v[100:101], 2, v[48:49]
	v_lshl_add_u64 v[50:51], s[0:1], 0, v[98:99]
	v_lshl_add_u64 v[66:67], s[0:1], 0, v[100:101]
	v_readlane_b32 s0, v255, 23
	s_ashr_i32 s11, s0, 31
	v_readlane_b32 s1, v255, 24
	s_mov_b32 s10, s0
	s_add_u32 s0, s94, s52
	v_ashrrev_i32_e32 v65, 31, v64
	v_lshl_add_u64 v[52:53], s[2:3], 0, v[98:99]
	s_addc_u32 s1, s95, s33
	v_lshlrev_b64 v[64:65], 4, v[64:65]
	global_load_dwordx4 v[32:35], v[50:51], off offset:16
	global_load_dwordx4 v[36:39], v[50:51], off
	global_load_dwordx4 v[40:43], v[52:53], off offset:16
	global_load_dwordx4 v[44:47], v[52:53], off
	v_lshl_add_u64 v[68:69], s[2:3], 0, v[100:101]
	global_load_dwordx4 v[48:51], v[66:67], off offset:16
	global_load_dwordx4 v[52:55], v[66:67], off
	global_load_dwordx4 v[56:59], v[68:69], off offset:16
	global_load_dwordx4 v[60:63], v[68:69], off
	v_lshl_add_u64 v[66:67], s[0:1], 0, v[64:65]
	s_mov_b64 s[0:1], 0x1000
	s_movk_i32 s2, 0x1000
	v_lshl_add_u64 v[68:69], v[66:67], 0, s[0:1]
	v_add_co_u32_e32 v66, vcc, s2, v66
	s_lshl_b64 s[2:3], s[10:11], 13
	s_nop 0
	v_addc_co_u32_e32 v67, vcc, 0, v67, vcc
	global_load_dwordx4 v[88:91], v[68:69], off offset:1024
	global_load_dwordx4 v[84:87], v[68:69], off offset:2048
	global_load_dwordx4 v[92:95], v[66:67], off
	global_load_dwordx4 v[80:83], v[68:69], off offset:3072
	v_and_b32_e32 v66, 64, v202
	v_add_u32_e32 v66, 64, v66
	v_cmp_lt_i32_e32 vcc, v203, v66
	s_add_u32 s2, s92, s2
	v_readlane_b32 s4, v255, 21
	v_cndmask_b32_e32 v67, v202, v203, vcc
	v_cmp_lt_i32_e32 vcc, v254, v66
	v_lshlrev_b32_e32 v104, 2, v67
	s_addc_u32 s3, s93, s3
	v_cndmask_b32_e32 v67, v202, v254, vcc
	v_lshlrev_b32_e32 v105, 2, v67
	v_xor_b32_e32 v67, 4, v202
	v_cmp_lt_i32_e32 vcc, v67, v66
	v_readlane_b32 s5, v255, 22
	s_mov_b32 s6, s4
	v_cndmask_b32_e32 v67, v202, v67, vcc
	v_lshlrev_b32_e32 v106, 2, v67
	v_xor_b32_e32 v67, 8, v202
	v_cmp_lt_i32_e32 vcc, v67, v66
	s_ashr_i32 s7, s4, 31
	s_lshl_b64 s[4:5], s[6:7], 13
	v_cndmask_b32_e32 v67, v202, v67, vcc
	v_lshlrev_b32_e32 v107, 2, v67
	v_xor_b32_e32 v67, 16, v202
	v_cmp_lt_i32_e32 vcc, v67, v66
	s_mov_b32 s14, s6
	s_add_i32 s6, s10, s6
	v_cndmask_b32_e32 v67, v202, v67, vcc
	s_mul_hi_i32 s7, s6, 0x3000
	s_mulk_i32 s6, 0x3000
	v_lshlrev_b32_e32 v108, 2, v67
	v_xor_b32_e32 v67, 32, v202
	s_add_u32 s6, s94, s6
	v_cmp_lt_i32_e32 vcc, v67, v66
	s_addc_u32 s7, s95, s7
	v_lshl_add_u64 v[64:65], s[6:7], 0, v[64:65]
	v_cndmask_b32_e32 v66, v202, v67, vcc
	v_lshlrev_b32_e32 v109, 2, v66
	v_lshl_add_u64 v[102:103], v[64:65], 0, s[0:1]
	s_mov_b32 s8, 0xba000000
	v_mov_b32_e32 v110, 0x3727c5ac
	s_mov_b32 s9, 0xf800000
	v_mov_b32_e32 v111, 0x260
	v_mbcnt_lo_u32_b32 v112, -1, 0
	v_mbcnt_hi_u32_b32 v112, -1, v112
	v_lshrrev_b32_e32 v112, 5, v112
	v_mul_u32_u24_e32 v112, 0x3f0, v112
	v_sub_u32_e32 v96, v96, v112
	v_sub_u32_e32 v98, v98, v112
	v_sub_u32_e32 v100, v100, v112
	s_branch .LBB0_1050
.LBB0_1049:
	s_waitcnt vmcnt(1)
	v_cvt_f32_f16_sdwa v112, v92 dst_sel:DWORD dst_unused:UNUSED_PAD src0_sel:WORD_1
	v_cvt_f32_f16_e32 v114, v92
	v_cvt_f32_f16_sdwa v116, v93 dst_sel:DWORD dst_unused:UNUSED_PAD src0_sel:WORD_1
	v_cvt_f32_f16_e32 v118, v93
	v_cvt_f32_f16_sdwa v113, v94 dst_sel:DWORD dst_unused:UNUSED_PAD src0_sel:WORD_1
	v_cvt_f32_f16_e32 v115, v94
	v_cvt_f32_f16_sdwa v117, v95 dst_sel:DWORD dst_unused:UNUSED_PAD src0_sel:WORD_1
	v_cvt_f32_f16_e32 v119, v95
	v_cvt_f32_f16_sdwa v120, v88 dst_sel:DWORD dst_unused:UNUSED_PAD src0_sel:WORD_1
	v_cvt_f32_f16_e32 v122, v88
	v_cvt_f32_f16_sdwa v121, v89 dst_sel:DWORD dst_unused:UNUSED_PAD src0_sel:WORD_1
	v_cvt_f32_f16_e32 v123, v89
	v_pk_add_f32 v[112:113], v[114:115], v[112:113]
	v_pk_add_f32 v[114:115], v[118:119], v[116:117]
	v_cvt_f32_f16_sdwa v126, v90 dst_sel:DWORD dst_unused:UNUSED_PAD src0_sel:WORD_1
	v_cvt_f32_f16_e32 v128, v90
	v_cvt_f32_f16_sdwa v134, v91 dst_sel:DWORD dst_unused:UNUSED_PAD src0_sel:WORD_1
	v_cvt_f32_f16_e32 v136, v91
	v_cvt_f32_f16_sdwa v138, v84 dst_sel:DWORD dst_unused:UNUSED_PAD src0_sel:WORD_1
	v_pk_add_f32 v[112:113], v[112:113], v[114:115]
	v_cvt_f32_f16_e32 v125, v84
	v_cvt_f32_f16_sdwa v127, v85 dst_sel:DWORD dst_unused:UNUSED_PAD src0_sel:WORD_1
	v_cvt_f32_f16_e32 v129, v85
	v_add_f32_e32 v112, 0, v112
	v_cvt_f32_f16_sdwa v130, v86 dst_sel:DWORD dst_unused:UNUSED_PAD src0_sel:WORD_1
	v_cvt_f32_f16_e32 v132, v86
	v_cvt_f32_f16_sdwa v131, v87 dst_sel:DWORD dst_unused:UNUSED_PAD src0_sel:WORD_1
	v_cvt_f32_f16_e32 v133, v87
	v_add_f32_e32 v124, v112, v113
	v_pk_add_f32 v[112:113], v[122:123], v[120:121]
	s_waitcnt vmcnt(0)
	v_cvt_f32_f16_sdwa v139, v80 dst_sel:DWORD dst_unused:UNUSED_PAD src0_sel:WORD_1
	v_pk_add_f32 v[112:113], v[112:113], v[112:113] op_sel:[0,1] op_sel_hi:[1,0]
	v_cvt_f32_f16_e32 v140, v80
	v_cvt_f32_f16_sdwa v141, v81 dst_sel:DWORD dst_unused:UNUSED_PAD src0_sel:WORD_1
	v_cvt_f32_f16_e32 v142, v81
	v_cvt_f32_f16_sdwa v143, v82 dst_sel:DWORD dst_unused:UNUSED_PAD src0_sel:WORD_1
	v_cvt_f32_f16_e32 v144, v82
	v_add_f32_e32 v128, v126, v128
	v_add_f32_e32 v126, v134, v136
	v_mov_b32_e32 v113, v138
	v_cvt_f32_f16_sdwa v135, v83 dst_sel:DWORD dst_unused:UNUSED_PAD src0_sel:WORD_1
	v_cvt_f32_f16_e32 v137, v83
	v_pk_add_f32 v[112:113], v[124:125], v[112:113]
	v_pk_add_f32 v[114:115], v[128:129], v[126:127]
	v_add_f32_e32 v136, v139, v140
	v_pk_add_f32 v[112:113], v[112:113], v[114:115]
	v_pk_add_f32 v[114:115], v[132:133], v[130:131]
	v_pk_add_f32 v[112:113], v[112:113], v[112:113] op_sel:[0,1] op_sel_hi:[1,0]
	v_pk_add_f32 v[114:115], v[114:115], v[114:115] op_sel:[0,1] op_sel_hi:[1,0]
	v_add_f32_e32 v134, v141, v142
	v_mov_b32_e32 v113, v144
	v_mov_b32_e32 v115, v143
	v_pk_add_f32 v[112:113], v[112:113], v[114:115]
	v_pk_add_f32 v[114:115], v[136:137], v[134:135]
	v_lshl_add_u64 v[102:103], v[102:103], 0, s[12:13]
	v_pk_add_f32 v[112:113], v[112:113], v[114:115]
	s_nop 0
	v_add_f32_e32 v112, v112, v113
	ds_bpermute_b32 v113, v104, v112
	s_waitcnt lgkmcnt(0)
	v_add_f32_e32 v112, v112, v113
	ds_bpermute_b32 v113, v105, v112
	s_waitcnt lgkmcnt(0)
	v_add_f32_e32 v112, v112, v113
	ds_bpermute_b32 v113, v106, v112
	s_waitcnt lgkmcnt(0)
	v_add_f32_e32 v112, v112, v113
	ds_bpermute_b32 v113, v107, v112
	s_waitcnt lgkmcnt(0)
	v_add_f32_e32 v112, v112, v113
	ds_bpermute_b32 v113, v108, v112
	s_waitcnt lgkmcnt(0)
	v_add_f32_e32 v112, v112, v113
	ds_bpermute_b32 v113, v109, v112
	s_waitcnt lgkmcnt(0)
	v_add_f32_e32 v134, v112, v113
	v_fma_mix_f32 v113, v134, s8, v93 op_sel:[0,0,1] op_sel_hi:[0,0,1]
	v_fma_mix_f32 v112, v134, s8, v93 op_sel_hi:[0,0,1]
	v_fma_mix_f32 v93, v134, s8, v92 op_sel:[0,0,1] op_sel_hi:[0,0,1]
	v_fma_mix_f32 v115, v134, s8, v95 op_sel:[0,0,1] op_sel_hi:[0,0,1]
	v_fma_mix_f32 v114, v134, s8, v95 op_sel_hi:[0,0,1]
	v_fma_mix_f32 v95, v134, s8, v94 op_sel:[0,0,1] op_sel_hi:[0,0,1]
	v_fma_mix_f32 v92, v134, s8, v92 op_sel_hi:[0,0,1]
	v_fma_mix_f32 v94, v134, s8, v94 op_sel_hi:[0,0,1]
	v_mov_b32_e32 v118, v93
	v_mov_b32_e32 v119, v95
	v_mov_b32_e32 v116, v92
	v_mov_b32_e32 v117, v94
	v_pk_mul_f32 v[118:119], v[118:119], v[118:119]
	v_mov_b32_e32 v120, v113
	v_mov_b32_e32 v121, v115
	v_pk_fma_f32 v[116:117], v[116:117], v[116:117], v[118:119]
	v_mov_b32_e32 v118, v112
	v_mov_b32_e32 v119, v114
	v_pk_mul_f32 v[120:121], v[120:121], v[120:121]
	v_fma_mix_f32 v127, v134, s8, v84 op_sel:[0,0,1] op_sel_hi:[0,0,1]
	v_pk_fma_f32 v[118:119], v[118:119], v[118:119], v[120:121]
	v_fma_mix_f32 v121, v134, s8, v89 op_sel:[0,0,1] op_sel_hi:[0,0,1]
	v_pk_add_f32 v[116:117], v[116:117], v[118:119]
	v_fma_mix_f32 v119, v134, s8, v88 op_sel:[0,0,1] op_sel_hi:[0,0,1]
	v_fma_mix_f32 v118, v134, s8, v88 op_sel_hi:[0,0,1]
	v_fma_mix_f32 v120, v134, s8, v89 op_sel_hi:[0,0,1]
	v_pk_mul_f32 v[88:89], v[120:121], v[120:121]
	v_pk_mul_f32 v[122:123], v[118:119], v[118:119]
	v_fma_mix_f32 v126, v134, s8, v84 op_sel_hi:[0,0,1]
	v_pk_mov_b32 v[124:125], v[122:123], v[88:89] op_sel:[1,0]
	v_mov_b32_e32 v123, v89
	v_pk_add_f32 v[88:89], v[124:125], v[122:123]
	v_fma_mix_f32 v123, v134, s8, v90 op_sel:[0,0,1] op_sel_hi:[0,0,1]
	v_fma_mix_f32 v122, v134, s8, v90 op_sel_hi:[0,0,1]
	v_fma_mix_f32 v125, v134, s8, v91 op_sel:[0,0,1] op_sel_hi:[0,0,1]
	v_fma_mix_f32 v124, v134, s8, v91 op_sel_hi:[0,0,1]
	v_fma_mix_f32 v91, v134, s8, v85 op_sel:[0,0,1] op_sel_hi:[0,0,1]
	v_fma_mix_f32 v90, v134, s8, v85 op_sel_hi:[0,0,1]
	v_mul_f32_e32 v128, v126, v126
	v_mul_f32_e32 v129, v127, v127
	v_pk_add_f32 v[84:85], v[116:117], v[116:117] op_sel:[0,1] op_sel_hi:[1,0]
	v_pk_add_f32 v[88:89], v[88:89], v[88:89] op_sel:[0,1] op_sel_hi:[1,0]
	v_mov_b32_e32 v85, v128
	v_mov_b32_e32 v89, v129
	v_pk_add_f32 v[84:85], v[84:85], v[88:89]
	v_mul_f32_e32 v88, v123, v123
	v_mul_f32_e32 v116, v125, v125
	v_mul_f32_e32 v130, v90, v90
	v_mul_f32_e32 v131, v91, v91
	v_pk_fma_f32 v[88:89], v[122:123], v[122:123], v[88:89] op_sel_hi:[1,1,0]
	v_pk_fma_f32 v[116:117], v[124:125], v[124:125], v[116:117] op_sel_hi:[1,1,0]
	v_mov_b32_e32 v89, v130
	v_mov_b32_e32 v117, v131
	v_pk_add_f32 v[88:89], v[88:89], v[116:117]
	v_fma_mix_f32 v117, v134, s8, v87 op_sel:[0,0,1] op_sel_hi:[0,0,1]
	v_pk_add_f32 v[84:85], v[84:85], v[88:89]
	v_fma_mix_f32 v89, v134, s8, v86 op_sel:[0,0,1] op_sel_hi:[0,0,1]
	v_fma_mix_f32 v88, v134, s8, v86 op_sel_hi:[0,0,1]
	v_fma_mix_f32 v116, v134, s8, v87 op_sel_hi:[0,0,1]
	v_pk_mul_f32 v[86:87], v[116:117], v[116:117]
	v_pk_mul_f32 v[128:129], v[88:89], v[88:89]
	v_fma_mix_f32 v133, v134, s8, v83 op_sel:[0,0,1] op_sel_hi:[0,0,1]
	v_pk_mov_b32 v[130:131], v[128:129], v[86:87] op_sel:[1,0]
	v_mov_b32_e32 v129, v87
	v_pk_add_f32 v[86:87], v[130:131], v[128:129]
	v_fma_mix_f32 v129, v134, s8, v80 op_sel:[0,0,1] op_sel_hi:[0,0,1]
	v_fma_mix_f32 v128, v134, s8, v80 op_sel_hi:[0,0,1]
	v_fma_mix_f32 v131, v134, s8, v81 op_sel:[0,0,1] op_sel_hi:[0,0,1]
	v_fma_mix_f32 v130, v134, s8, v81 op_sel_hi:[0,0,1]
	v_fma_mix_f32 v132, v134, s8, v83 op_sel_hi:[0,0,1]
	v_fma_mix_f32 v135, v134, s8, v82 op_sel:[0,0,1] op_sel_hi:[0,0,1]
	v_fma_mix_f32 v134, v134, s8, v82 op_sel_hi:[0,0,1]
	v_mul_f32_e32 v82, v134, v134
	v_pk_add_f32 v[80:81], v[84:85], v[84:85] op_sel:[0,1] op_sel_hi:[1,0]
	v_mul_f32_e32 v136, v135, v135
	v_mov_b32_e32 v81, v82
	v_pk_add_f32 v[82:83], v[86:87], v[86:87] op_sel:[0,1] op_sel_hi:[1,0]
	v_mul_f32_e32 v84, v131, v131
	v_mov_b32_e32 v83, v136
	v_pk_add_f32 v[80:81], v[80:81], v[82:83]
	v_mul_f32_e32 v82, v129, v129
	v_mul_f32_e32 v137, v132, v132
	v_mul_f32_e32 v138, v133, v133
	v_pk_fma_f32 v[82:83], v[128:129], v[128:129], v[82:83] op_sel_hi:[1,1,0]
	v_pk_fma_f32 v[84:85], v[130:131], v[130:131], v[84:85] op_sel_hi:[1,1,0]
	v_mov_b32_e32 v83, v137
	v_mov_b32_e32 v85, v138
	v_pk_add_f32 v[82:83], v[82:83], v[84:85]
	s_nop 0
	v_pk_add_f32 v[80:81], v[80:81], v[82:83]
	s_nop 0
	v_add_f32_e32 v80, v80, v81
	ds_bpermute_b32 v81, v104, v80
	s_waitcnt lgkmcnt(0)
	v_add_f32_e32 v80, v80, v81
	ds_bpermute_b32 v81, v105, v80
	s_waitcnt lgkmcnt(0)
	v_add_f32_e32 v80, v80, v81
	ds_bpermute_b32 v81, v106, v80
	s_waitcnt lgkmcnt(0)
	v_add_f32_e32 v80, v80, v81
	ds_bpermute_b32 v81, v107, v80
	s_waitcnt lgkmcnt(0)
	v_add_f32_e32 v80, v80, v81
	ds_bpermute_b32 v81, v108, v80
	s_waitcnt lgkmcnt(0)
	v_add_f32_e32 v80, v80, v81
	ds_bpermute_b32 v81, v109, v80
	s_waitcnt lgkmcnt(0)
	v_add_f32_e32 v80, v80, v81
	v_fmamk_f32 v80, v80, 0x3a000000, v110
	v_mul_f32_e32 v81, 0x4f800000, v80
	v_cmp_gt_f32_e32 vcc, s9, v80
	s_nop 1
	v_cndmask_b32_e32 v80, v80, v81, vcc
	v_sqrt_f32_e32 v81, v80
	s_nop 0
	v_add_u32_e32 v82, -1, v81
	v_fma_f32 v83, -v82, v81, v80
	v_cmp_ge_f32_e64 s[0:1], 0, v83
	v_add_u32_e32 v83, 1, v81
	s_nop 0
	v_cndmask_b32_e64 v82, v81, v82, s[0:1]
	v_fma_f32 v81, -v83, v81, v80
	v_cmp_lt_f32_e64 s[0:1], 0, v81
	s_nop 1
	v_cndmask_b32_e64 v81, v82, v83, s[0:1]
	v_mul_f32_e32 v82, 0x37800000, v81
	v_cndmask_b32_e32 v81, v81, v82, vcc
	v_cmp_class_f32_e32 vcc, v80, v111
	s_nop 1
	v_cndmask_b32_e32 v80, v81, v80, vcc
	v_div_scale_f32 v81, s[0:1], v80, v80, 1.0
	v_rcp_f32_e32 v82, v81
	s_nop 0
	v_fma_f32 v83, -v81, v82, 1.0
	v_fmac_f32_e32 v82, v83, v82
	v_div_scale_f32 v83, vcc, 1.0, v80, 1.0
	v_mul_f32_e32 v84, v83, v82
	v_fma_f32 v85, -v81, v84, v83
	v_fmac_f32_e32 v84, v85, v82
	v_fma_f32 v81, -v81, v84, v83
	v_div_fmas_f32 v81, v81, v82, v84
	v_div_fixup_f32 v136, v81, v80, 1.0
	v_pk_mul_f32 v[80:81], v[136:137], v[92:93] op_sel_hi:[0,1]
	v_pk_mul_f32 v[82:83], v[136:137], v[112:113] op_sel_hi:[0,1]
	v_pk_mul_f32 v[84:85], v[136:137], v[94:95] op_sel_hi:[0,1]
	v_pk_mul_f32 v[86:87], v[136:137], v[114:115] op_sel_hi:[0,1]
	v_pk_fma_f32 v[82:83], v[82:83], v[6:7], v[14:15]
	v_pk_fma_f32 v[80:81], v[80:81], v[4:5], v[12:13]
	v_pk_fma_f32 v[86:87], v[86:87], v[2:3], v[10:11]
	v_pk_fma_f32 v[84:85], v[84:85], v[0:1], v[8:9]
	v_lshl_add_u64 v[92:93], s[2:3], 0, v[96:97]
	s_nop 1
	v_permlane32_swap_b32_e32 v80, v84
	v_permlane32_swap_b32_e32 v81, v85
	v_permlane32_swap_b32_e32 v82, v86
	v_permlane32_swap_b32_e32 v83, v87
	global_store_dwordx4 v[92:93], v[80:83], off
	global_store_dwordx4 v[92:93], v[84:87], off offset:1024
	s_nop 0
	v_pk_mul_f32 v[80:81], v[136:137], v[118:119] op_sel_hi:[0,1]
	v_pk_mul_f32 v[82:83], v[136:137], v[120:121] op_sel_hi:[0,1]
	v_pk_mul_f32 v[84:85], v[136:137], v[122:123] op_sel_hi:[0,1]
	v_pk_mul_f32 v[86:87], v[136:137], v[124:125] op_sel_hi:[0,1]
	v_pk_fma_f32 v[82:83], v[82:83], v[22:23], v[30:31]
	v_pk_fma_f32 v[80:81], v[80:81], v[20:21], v[28:29]
	v_pk_fma_f32 v[86:87], v[86:87], v[18:19], v[26:27]
	v_pk_fma_f32 v[84:85], v[84:85], v[16:17], v[24:25]
	s_nop 1
	v_permlane32_swap_b32_e32 v80, v84
	v_permlane32_swap_b32_e32 v81, v85
	v_permlane32_swap_b32_e32 v82, v86
	v_permlane32_swap_b32_e32 v83, v87
	global_store_dwordx4 v[92:93], v[80:83], off offset:2048
	global_store_dwordx4 v[92:93], v[84:87], off offset:3072
	v_mov_b64_e32 v[94:95], v[78:79]
	v_pk_mul_f32 v[80:81], v[136:137], v[126:127] op_sel_hi:[0,1]
	v_pk_mul_f32 v[82:83], v[136:137], v[90:91] op_sel_hi:[0,1]
	v_pk_mul_f32 v[84:85], v[136:137], v[88:89] op_sel_hi:[0,1]
	v_pk_mul_f32 v[86:87], v[136:137], v[116:117] op_sel_hi:[0,1]
	v_pk_fma_f32 v[82:83], v[82:83], v[38:39], v[46:47]
	v_pk_fma_f32 v[80:81], v[80:81], v[36:37], v[44:45]
	v_pk_fma_f32 v[86:87], v[86:87], v[34:35], v[42:43]
	v_pk_fma_f32 v[84:85], v[84:85], v[32:33], v[40:41]
	v_lshl_add_u64 v[88:89], s[2:3], 0, v[98:99]
	s_nop 1
	v_permlane32_swap_b32_e32 v80, v84
	v_permlane32_swap_b32_e32 v81, v85
	v_permlane32_swap_b32_e32 v82, v86
	v_permlane32_swap_b32_e32 v83, v87
	global_store_dwordx4 v[88:89], v[80:83], off
	global_store_dwordx4 v[88:89], v[84:87], off offset:1024
	v_lshl_add_u64 v[88:89], s[2:3], 0, v[100:101]
	v_pk_mul_f32 v[80:81], v[136:137], v[128:129] op_sel_hi:[0,1]
	v_pk_mul_f32 v[82:83], v[136:137], v[130:131] op_sel_hi:[0,1]
	v_pk_mul_f32 v[84:85], v[136:137], v[134:135] op_sel_hi:[0,1]
	v_pk_mul_f32 v[86:87], v[136:137], v[132:133] op_sel_hi:[0,1]
	v_pk_fma_f32 v[82:83], v[82:83], v[54:55], v[62:63]
	v_pk_fma_f32 v[80:81], v[80:81], v[52:53], v[60:61]
	v_pk_fma_f32 v[86:87], v[86:87], v[50:51], v[58:59]
	v_pk_fma_f32 v[84:85], v[84:85], v[48:49], v[56:57]
	s_nop 1
	v_permlane32_swap_b32_e32 v80, v84
	v_permlane32_swap_b32_e32 v81, v85
	v_permlane32_swap_b32_e32 v82, v86
	v_permlane32_swap_b32_e32 v83, v87
	global_store_dwordx4 v[88:89], v[80:83], off
	global_store_dwordx4 v[88:89], v[84:87], off offset:1024
	s_add_u32 s2, s2, s4
	v_mov_b64_e32 v[82:83], v[66:67]
	v_mov_b64_e32 v[86:87], v[70:71]
	v_mov_b64_e32 v[90:91], v[74:75]
	s_addc_u32 s3, s3, s5
	s_andn2_b64 vcc, exec, s[6:7]
	v_mov_b64_e32 v[80:81], v[64:65]
	v_mov_b64_e32 v[84:85], v[68:69]
	v_mov_b64_e32 v[88:89], v[72:73]
	v_mov_b64_e32 v[92:93], v[76:77]
	s_cbranch_vccz .LBB0_1052
